# phase 3 queue: prompt diff-attention items request the next ticket at the start of their finalize, the following pop consumes it (no atomic round trip at item start)
# baseline (speedup 1.0000x reference)
.LBB0_995:
	s_cmp_lt_i32 s56, 4
	s_cselect_b64 s[2:3], -1, 0
	s_and_b64 s[0:1], s[2:3], s[0:1]
	s_andn2_b64 vcc, exec, s[0:1]
	s_cbranch_vccnz .LBB0_1110
	s_bfe_u32 s55, s58, 0x10003
	v_writelane_b32 v255, s2, 44
	s_add_u32 s0, s96, 0x2904c300
	s_addc_u32 s1, s97, 0
	v_writelane_b32 v255, s3, 45
	v_writelane_b32 v255, s0, 4
	v_readlane_b32 s20, v253, 1
	v_readlane_b32 s24, v253, 5
	v_writelane_b32 v255, s1, 5
	s_add_u32 s0, s96, 0x2904c500
	s_addc_u32 s1, s97, 0
	v_writelane_b32 v254, s0, 62
	v_readlane_b32 s25, v253, 6
	v_readlane_b32 s26, v253, 7
	v_writelane_b32 v254, s1, 63
	s_add_u32 s0, s96, 0x2904c600
	s_addc_u32 s1, s97, 0
	v_writelane_b32 v255, s0, 0
	v_readlane_b32 s27, v253, 8
	s_mov_b64 s[12:13], s[24:25]
	v_writelane_b32 v255, s1, 1
	s_add_u32 s0, s96, 0x2904c700
	s_addc_u32 s1, s97, 0
	s_add_u32 s60, s96, 0x2904c800
	s_addc_u32 s61, s97, 0
	s_add_u32 s62, s96, 0x2904c900
	s_addc_u32 s63, s97, 0
	s_add_u32 s80, s96, 0x2904ca00
	s_addc_u32 s81, s97, 0
	s_add_u32 s94, s96, 0x2904cb00
	s_addc_u32 s95, s97, 0
	s_add_u32 s56, s96, 0x2904cc00
	s_addc_u32 s57, s97, 0
	s_add_u32 s58, s96, 0x2904cd00
	s_addc_u32 s59, s97, 0
	s_add_u32 s82, s96, 0x2904ce00
	s_addc_u32 s83, s97, 0
	s_add_u32 s84, s96, 0x2904cf00
	s_addc_u32 s85, s97, 0
	s_add_u32 s86, s96, 0x2904d000
	s_addc_u32 s87, s97, 0
	s_add_u32 s88, s96, 0x2904d100
	s_addc_u32 s89, s97, 0
	s_add_u32 s90, s96, 0x2904d200
	s_addc_u32 s91, s97, 0
	s_add_u32 s92, s96, 0x2904d300
	s_addc_u32 s93, s97, 0
	v_writelane_b32 v255, s0, 2
	s_add_u32 s2, s96, 0x2904d400
	s_addc_u32 s3, s97, 0
	v_writelane_b32 v255, s1, 3
	v_readlane_b32 s0, v253, 18
	s_cmp_eq_u32 s0, 15
	s_cselect_b64 s[4:5], -1, 0
	v_writelane_b32 v254, s4, 12
	s_cmp_eq_u32 s0, 14
	s_mov_b64 s[14:15], s[26:27]
	v_writelane_b32 v254, s5, 13
	s_cselect_b64 s[4:5], -1, 0
	v_writelane_b32 v254, s4, 14
	s_cmp_eq_u32 s0, 13
	v_readlane_b32 s21, v253, 2
	v_writelane_b32 v254, s5, 15
	s_cselect_b64 s[4:5], -1, 0
	v_writelane_b32 v254, s4, 16
	s_cmp_eq_u32 s0, 12
	v_readlane_b32 s22, v253, 3
	v_writelane_b32 v254, s5, 17
	s_cselect_b64 s[4:5], -1, 0
	v_writelane_b32 v254, s4, 18
	s_cmp_eq_u32 s0, 11
	v_readlane_b32 s23, v253, 4
	v_writelane_b32 v254, s5, 19
	s_cselect_b64 s[4:5], -1, 0
	v_writelane_b32 v254, s4, 20
	s_cmp_eq_u32 s0, 10
	v_mbcnt_lo_u32_b32 v0, -1, 0
	v_writelane_b32 v254, s5, 21
	s_cselect_b64 s[4:5], -1, 0
	v_writelane_b32 v254, s4, 22
	s_cmp_eq_u32 s0, 9
	v_mov_b32_e32 v125, 0
	v_writelane_b32 v254, s5, 23
	s_cselect_b64 s[4:5], -1, 0
	v_writelane_b32 v254, s4, 24
	s_cmp_eq_u32 s0, 8
	v_mov_b32_e32 v160, 1
	v_writelane_b32 v254, s5, 25
	s_cselect_b64 s[4:5], -1, 0
	v_writelane_b32 v254, s4, 26
	s_cmp_eq_u32 s0, 7
	v_mov_b32_e32 v161, 0x2904a000
	v_writelane_b32 v254, s5, 27
	s_cselect_b64 s[4:5], -1, 0
	v_writelane_b32 v254, s4, 28
	s_cmp_eq_u32 s0, 6
	v_mov_b32_e32 v162, 0x358637bd
	v_writelane_b32 v254, s5, 29
	s_cselect_b64 s[4:5], -1, 0
	v_writelane_b32 v254, s4, 30
	s_cmp_eq_u32 s0, 5
	v_mbcnt_hi_u32_b32 v164, -1, v0
	v_writelane_b32 v254, s5, 31
	s_cselect_b64 s[4:5], -1, 0
	v_writelane_b32 v254, s4, 32
	s_cmp_eq_u32 s0, 4
	v_mov_b32_e32 v126, 0x3e0293ee
	v_writelane_b32 v254, s5, 33
	s_cselect_b64 s[4:5], -1, 0
	v_writelane_b32 v254, s4, 34
	s_cmp_eq_u32 s0, 3
	s_mov_b32 s6, 0x800000
	v_writelane_b32 v254, s5, 35
	s_cselect_b64 s[4:5], -1, 0
	v_writelane_b32 v254, s4, 36
	s_cmp_eq_u32 s0, 2
	s_movk_i32 s7, 0x210
	v_writelane_b32 v254, s5, 37
	s_cselect_b64 s[4:5], -1, 0
	v_writelane_b32 v254, s4, 38
	s_cmp_eq_u32 s0, 1
	s_movk_i32 s52, 0x90
	v_writelane_b32 v254, s5, 39
	s_cselect_b64 s[4:5], -1, 0
	v_writelane_b32 v254, s4, 42
	s_cmp_eq_u32 s0, 0
	s_movk_i32 s53, 0x1ff
	v_writelane_b32 v254, s5, 43
	s_cselect_b64 s[4:5], -1, 0
	v_writelane_b32 v254, s4, 6
	s_lshl_b32 s0, s0, 8
	s_mov_b32 s54, 0
	v_writelane_b32 v254, s5, 7
	v_readlane_b32 s4, v253, 16
	v_readlane_b32 s5, v253, 17
	s_add_u32 s0, s4, s0
	s_addc_u32 s1, s5, 0
	s_add_u32 s4, s0, 0x1400
	s_addc_u32 s5, s1, 0
	s_add_u32 s0, s0, 0x2400
	s_addc_u32 s1, s1, 0
	v_writelane_b32 v255, s0, 6
	v_writelane_b32 v254, s4, 10
	s_mov_b32 s27, 0
	v_writelane_b32 v255, s1, 7
	s_add_u32 s0, s96, 0x2904f500
	s_addc_u32 s1, s97, 0
	v_writelane_b32 v255, s0, 58
	v_writelane_b32 v254, s5, 11
	s_nop 0
	v_writelane_b32 v255, s1, 59
	s_add_u32 s0, s96, 0x2904f600
	s_addc_u32 s1, s97, 0
	v_writelane_b32 v254, s0, 44
	s_nop 1
	v_writelane_b32 v254, s1, 45
	s_add_u32 s0, s96, 0x2904c000
	s_addc_u32 s1, s97, 0
	s_add_u32 s44, s96, 0x2904c0c4
	s_addc_u32 s45, s97, 0
	s_add_u32 s9, s96, 0x28b08000
	s_addc_u32 s16, s97, 0
	s_add_u32 s46, s96, 0x19500000
	s_addc_u32 s47, s97, 0
	s_add_u32 s48, s96, 0x2100000
	s_addc_u32 s49, s97, 0
	s_add_u32 s17, s14, 0xce48000
	s_addc_u32 s18, s15, 0
	s_add_u32 s20, s96, 0xf000000
	s_addc_u32 s21, s97, 0
	s_add_u32 s22, s96, 0x11100000
	s_addc_u32 s23, s97, 0
	s_add_u32 s24, s96, 0xd000000
	s_addc_u32 s25, s97, 0
	s_add_u32 s19, s96, 0x1fb08000
	s_addc_u32 s42, s97, 0
	s_add_u32 s43, s96, 0x29048000
	s_addc_u32 s4, s97, 0
	v_writelane_b32 v255, s0, 8
	s_add_u32 s5, s14, 0xc200000
	s_addc_u32 s12, s15, 0
	v_writelane_b32 v255, s1, 9
	s_add_i32 s0, 0, 0x23fe0
	s_add_i32 s13, 0, 0x23ff0
	v_writelane_b32 v254, s0, 40
	s_add_i32 s0, 0, 0x23fe4
	v_mov_b32_e32 v163, s13
	v_writelane_b32 v254, s0, 8
	s_add_i32 s8, 0, 0x17c00
	s_movk_i32 s14, 0x200
	s_movk_i32 s15, 0x110
	s_mov_b32 s99, 0
	s_branch .LBB0_998

.LBB0_1053:
	s_mov_b32 s99, 0
	s_waitcnt vmcnt(0)
	s_ashr_i32 s29, s28, 31
	s_lshl_b64 s[0:1], s[28:29], 16
	s_add_u32 s0, s5, s0
	s_addc_u32 s1, s12, s1
	v_lshl_add_u64 v[32:33], v[64:65], 2, s[0:1]
	v_lshlrev_b32_e32 v124, 11, v71
	v_lshlrev_b32_e32 v38, 9, v108
	v_lshl_add_u64 v[34:35], v[32:33], 0, v[124:125]
	v_lshlrev_b32_e32 v124, 9, v111
	v_lshl_add_u64 v[36:37], v[32:33], 0, v[124:125]
	v_or_b32_e32 v124, 0x400, v38
	global_store_dword v[34:35], v28, off
	global_store_dword v[36:37], v29, off
	v_lshl_add_u64 v[28:29], v[32:33], 0, v[124:125]
	v_or_b32_e32 v124, 0x600, v38
	global_store_dword v[28:29], v30, off
	v_lshl_add_u64 v[28:29], v[32:33], 0, v[124:125]
	v_or_b32_e32 v124, 0x2000, v38
	global_store_dword v[28:29], v31, off
	v_lshl_add_u64 v[28:29], v[32:33], 0, v[124:125]
	v_or_b32_e32 v124, 0x2200, v38
	global_store_dword v[28:29], v20, off
	v_lshl_add_u64 v[28:29], v[32:33], 0, v[124:125]
	v_or_b32_e32 v124, 0x2400, v38
	global_store_dword v[28:29], v21, off
	v_lshl_add_u64 v[20:21], v[32:33], 0, v[124:125]
	v_or_b32_e32 v124, 0x2600, v38
	global_store_dword v[20:21], v22, off
	v_lshl_add_u64 v[20:21], v[32:33], 0, v[124:125]
	v_or_b32_e32 v124, 0x4000, v38
	global_store_dword v[20:21], v23, off
	v_lshl_add_u64 v[20:21], v[32:33], 0, v[124:125]
	v_or_b32_e32 v124, 0x4200, v38
	global_store_dword v[20:21], v0, off
	v_lshl_add_u64 v[20:21], v[32:33], 0, v[124:125]
	v_or_b32_e32 v124, 0x4400, v38
	global_store_dword v[20:21], v1, off
	v_lshl_add_u64 v[0:1], v[32:33], 0, v[124:125]
	v_or_b32_e32 v124, 0x4600, v38
	global_store_dword v[0:1], v2, off
	v_lshl_add_u64 v[0:1], v[32:33], 0, v[124:125]
	v_or_b32_e32 v124, 0x6000, v38
	global_store_dword v[0:1], v3, off
	v_lshl_add_u64 v[0:1], v[32:33], 0, v[124:125]
	v_or_b32_e32 v124, 0x6200, v38
	global_store_dword v[0:1], v16, off
	v_lshl_add_u64 v[0:1], v[32:33], 0, v[124:125]
	v_or_b32_e32 v124, 0x6400, v38
	global_store_dword v[0:1], v17, off
	v_lshl_add_u64 v[0:1], v[32:33], 0, v[124:125]
	v_or_b32_e32 v124, 0x6600, v38
	global_store_dword v[0:1], v18, off
	v_lshl_add_u64 v[0:1], v[32:33], 0, v[124:125]
	s_mov_b32 s0, 0x8000
	global_store_dword v[0:1], v19, off
	v_add_co_u32_e32 v0, vcc, s0, v34
	s_mov_b32 s0, 0xa000
	s_nop 0
	v_addc_co_u32_e32 v1, vcc, 0, v35, vcc
	global_store_dword v[0:1], v4, off
	global_store_dword v[0:1], v5, off offset:512
	global_store_dword v[0:1], v6, off offset:1024
	global_store_dword v[0:1], v7, off offset:1536
	v_add_co_u32_e32 v0, vcc, s0, v34
	s_nop 1
	v_addc_co_u32_e32 v1, vcc, 0, v35, vcc
	global_store_dword v[0:1], v12, off
	global_store_dword v[0:1], v13, off offset:512
	global_store_dword v[0:1], v14, off offset:1024
	global_store_dword v[0:1], v15, off offset:1536
	v_add_co_u32_e32 v0, vcc, 0xc000, v34
	s_nop 1
	v_addc_co_u32_e32 v1, vcc, 0, v35, vcc
	global_store_dword v[0:1], v8, off
	global_store_dword v[0:1], v9, off offset:512
	global_store_dword v[0:1], v10, off offset:1024
	global_store_dword v[0:1], v11, off offset:1536
	v_add_co_u32_e32 v0, vcc, 0xe000, v34
	s_nop 1
	v_addc_co_u32_e32 v1, vcc, 0, v35, vcc
	global_store_dword v[0:1], v24, off
	global_store_dword v[0:1], v25, off offset:512
	global_store_dword v[0:1], v26, off offset:1024
	global_store_dword v[0:1], v27, off offset:1536

.LBB0_1056:
	v_mov_b32_e32 v0, v230
	s_barrier
	s_nop 0
	v_cmp_eq_u32_e32 vcc, 0, v0
	s_and_saveexec_b64 s[0:1], vcc
	s_cbranch_execz .LBB0_1060
	s_cmp_eq_u32 s99, 0
	s_cbranch_scc1 .Lpop3_fresh
	s_mov_b32 s99, 0
	s_waitcnt vmcnt(0)
	v_readfirstlane_b32 s10, v252
	s_branch .Lpop3_have
.Lpop3_fresh:
	v_mov_b32_e32 v1, 1
	global_atomic_add v1, v125, v1, s[44:45] sc0
	s_waitcnt vmcnt(0)
	v_readfirstlane_b32 s10, v1
.Lpop3_have:
	v_mov_b32_e32 v1, s13
	s_nop 0
	v_mov_b32_e32 v0, s10
	ds_write_b32 v1, v0

.LBB0_1084:
	v_cmp_eq_u32_e64 s[100:101], 0, v230
	s_nop 1
	s_and_saveexec_b64 s[100:101], s[100:101]
	v_mov_b32_e32 v252, 1
	global_atomic_add v252, v125, v252, s[44:45] sc0
	s_mov_b64 exec, s[100:101]
	s_mov_b32 s99, 1
	ds_bpermute_b32 v0, v139, v113
	s_cmp_eq_u32 s0, 0
	s_waitcnt lgkmcnt(0)
	s_barrier
	v_add_f32_e32 v0, v113, v0
	ds_bpermute_b32 v1, v140, v0
	s_waitcnt lgkmcnt(0)
	v_add_f32_e32 v0, v0, v1
	v_div_scale_f32 v1, s[30:31], v0, v0, 1.0
	v_rcp_f32_e32 v2, v1
	v_div_scale_f32 v3, vcc, 1.0, v0, 1.0
	s_cselect_b64 s[30:31], -1, 0
	v_fma_f32 v4, -v1, v2, 1.0
	v_fmac_f32_e32 v2, v4, v2
	v_mul_f32_e32 v4, v3, v2
	v_fma_f32 v5, -v1, v4, v3
	v_fmac_f32_e32 v4, v5, v2
	v_fma_f32 v1, -v1, v4, v3
	v_div_fmas_f32 v1, v1, v2, v4
	v_div_fixup_f32 v4, v1, v0, 1.0
	v_pk_mul_f32 v[108:109], v[108:109], v[4:5] op_sel_hi:[1,0]
	v_pk_mul_f32 v[110:111], v[110:111], v[4:5] op_sel_hi:[1,0]
	v_pk_mul_f32 v[104:105], v[104:105], v[4:5] op_sel_hi:[1,0]
	v_pk_mul_f32 v[106:107], v[106:107], v[4:5] op_sel_hi:[1,0]
	v_pk_mul_f32 v[100:101], v[100:101], v[4:5] op_sel_hi:[1,0]
	v_pk_mul_f32 v[102:103], v[102:103], v[4:5] op_sel_hi:[1,0]
	v_pk_mul_f32 v[92:93], v[92:93], v[4:5] op_sel_hi:[1,0]
	v_pk_mul_f32 v[94:95], v[94:95], v[4:5] op_sel_hi:[1,0]
	s_waitcnt vmcnt(0)
	v_pk_mul_f32 v[44:45], v[96:97], v[4:5] op_sel_hi:[1,0]
	v_pk_mul_f32 v[46:47], v[98:99], v[4:5] op_sel_hi:[1,0]
	v_pk_mul_f32 v[40:41], v[88:89], v[4:5] op_sel_hi:[1,0]
	v_pk_mul_f32 v[42:43], v[90:91], v[4:5] op_sel_hi:[1,0]
	v_pk_mul_f32 v[36:37], v[84:85], v[4:5] op_sel_hi:[1,0]
	v_pk_mul_f32 v[38:39], v[86:87], v[4:5] op_sel_hi:[1,0]
	v_pk_mul_f32 v[32:33], v[80:81], v[4:5] op_sel_hi:[1,0]
	v_pk_mul_f32 v[34:35], v[82:83], v[4:5] op_sel_hi:[1,0]
	v_pk_mul_f32 v[28:29], v[76:77], v[4:5] op_sel_hi:[1,0]
	v_pk_mul_f32 v[30:31], v[78:79], v[4:5] op_sel_hi:[1,0]
	v_pk_mul_f32 v[24:25], v[72:73], v[4:5] op_sel_hi:[1,0]
	v_pk_mul_f32 v[26:27], v[74:75], v[4:5] op_sel_hi:[1,0]
	v_pk_mul_f32 v[20:21], v[68:69], v[4:5] op_sel_hi:[1,0]
	v_pk_mul_f32 v[22:23], v[70:71], v[4:5] op_sel_hi:[1,0]
	v_pk_mul_f32 v[16:17], v[64:65], v[4:5] op_sel_hi:[1,0]
	v_pk_mul_f32 v[18:19], v[66:67], v[4:5] op_sel_hi:[1,0]
	v_pk_mul_f32 v[12:13], v[60:61], v[4:5] op_sel_hi:[1,0]
	v_pk_mul_f32 v[14:15], v[62:63], v[4:5] op_sel_hi:[1,0]
	v_pk_mul_f32 v[8:9], v[56:57], v[4:5] op_sel_hi:[1,0]
	v_pk_mul_f32 v[10:11], v[58:59], v[4:5] op_sel_hi:[1,0]
	v_pk_mul_f32 v[0:1], v[52:53], v[4:5] op_sel_hi:[1,0]
	v_pk_mul_f32 v[2:3], v[54:55], v[4:5] op_sel_hi:[1,0]
	v_pk_mul_f32 v[6:7], v[48:49], v[4:5] op_sel_hi:[1,0]
	v_pk_mul_f32 v[4:5], v[50:51], v[4:5] op_sel_hi:[1,0]
	s_cmp_lg_u32 s0, 0
	v_lshlrev_b32_e32 v48, 8, v142
	v_lshlrev_b32_e32 v49, 2, v141
	s_cbranch_scc0 .LBB0_1086
	s_lshl_b32 s0, s11, 14
	s_add_i32 s0, s0, 0
	v_add3_u32 v50, s0, v49, v48
	v_add_u32_e32 v51, 0x400, v50
	ds_write2_b32 v50, v108, v109 offset1:16
	ds_write2_b32 v50, v110, v111 offset0:32 offset1:48
	ds_write2_b32 v51, v104, v105 offset1:16
	ds_write2_b32 v51, v106, v107 offset0:32 offset1:48
	v_add_u32_e32 v51, 0x800, v50
	ds_write2_b32 v51, v100, v101 offset1:16
	ds_write2_b32 v51, v102, v103 offset0:32 offset1:48
	v_add_u32_e32 v51, 0xc00, v50
	ds_write2_b32 v51, v92, v93 offset1:16
	ds_write2_b32 v51, v94, v95 offset0:32 offset1:48
	v_add_u32_e32 v51, 0x1000, v50
	ds_write2_b32 v51, v44, v45 offset1:16
	ds_write2_b32 v51, v46, v47 offset0:32 offset1:48
	v_add_u32_e32 v51, 0x1400, v50
	ds_write2_b32 v51, v40, v41 offset1:16
	ds_write2_b32 v51, v42, v43 offset0:32 offset1:48
	v_add_u32_e32 v51, 0x1800, v50
	ds_write2_b32 v51, v36, v37 offset1:16
	ds_write2_b32 v51, v38, v39 offset0:32 offset1:48
	v_add_u32_e32 v51, 0x1c00, v50
	ds_write2_b32 v51, v32, v33 offset1:16
	ds_write2_b32 v51, v34, v35 offset0:32 offset1:48
	v_add_u32_e32 v51, 0x2000, v50
	ds_write2_b32 v51, v28, v29 offset1:16
	ds_write2_b32 v51, v30, v31 offset0:32 offset1:48
	v_add_u32_e32 v51, 0x2400, v50
	ds_write2_b32 v51, v24, v25 offset1:16
	ds_write2_b32 v51, v26, v27 offset0:32 offset1:48
	v_add_u32_e32 v51, 0x2800, v50
	ds_write2_b32 v51, v20, v21 offset1:16
	ds_write2_b32 v51, v22, v23 offset0:32 offset1:48
	v_add_u32_e32 v51, 0x2c00, v50
	ds_write2_b32 v51, v16, v17 offset1:16
	ds_write2_b32 v51, v18, v19 offset0:32 offset1:48
	v_add_u32_e32 v51, 0x3000, v50
	ds_write2_b32 v51, v12, v13 offset1:16
	ds_write2_b32 v51, v14, v15 offset0:32 offset1:48
	v_add_u32_e32 v51, 0x3400, v50
	ds_write2_b32 v51, v8, v9 offset1:16
	ds_write2_b32 v51, v10, v11 offset0:32 offset1:48
	v_add_u32_e32 v51, 0x3800, v50
	v_add_u32_e32 v50, 0x3c00, v50
	ds_write2_b32 v51, v0, v1 offset1:16
	ds_write2_b32 v51, v2, v3 offset0:32 offset1:48
	ds_write2_b32 v50, v6, v7 offset1:16
	ds_write2_b32 v50, v4, v5 offset0:32 offset1:48
